# SwiGLU epilogue: the spacing nops between dependent packed ops now carry the next group's first multiplies (334 -> 319 instructions per tile-wave)
# baseline (speedup 1.0000x reference)
; __device__ __forceinline__ unsigned pk2(float lo, float hi) { const f32x2 v = {lo, hi}; const bf16x2n b = __builtin_convertvector(v, bf16x2n); return __builtin_bit_cast(unsigned, b); }
; __device__ __forceinline__ float siluf_(float x) { return x * rcp_(1.0f + __expf(-x)); }
;     __device__ __forceinline__ void operator()(const f32x4 (&acc)[2][2][4][2], const Unit& u, int wr, int wc, int fr, int fq) const {
;     ...
;                 bf16_t* rowp = H + (size_t)(row0 + ai * 128 + m * 16) * DFF + col0;
;                 const f32x4 g0 = acc[ai][0][m][0], g1 = acc[ai][0][m][1], u0 = acc[ai][1][m][0], u1 = acc[ai][1][m][1];
;                 float v[8];
; #pragma unroll
;                 for (int j = 0; j < 4; ++j) { v[j] = siluf_(g0[j]) * u0[j]; v[4 + j] = siluf_(g1[j]) * u1[j]; }
;                 u32x4 w; w.x = pk2(v[0], v[1]); w.y = pk2(v[2], v[3]); w.z = pk2(v[4], v[5]); w.w = pk2(v[6], v[7]);
;                 __builtin_nontemporal_store(w, (u32x4*)rowp);
.LBB0_787:
	v_lshl_or_b32 v148, s25, 7, v144
	v_lshl_add_u32 v146, s24, 8, v142
	v_ashrrev_i32_e32 v149, 31, v148
	v_mov_b64_e32 v[140:141], s[94:95]
	v_mov_b32_e32 v176, 0xbfb8aa3b
	v_lshlrev_b64 v[148:149], 1, v[148:149]
	v_mad_i64_i32 v[150:151], s[24:25], v146, s67, v[140:141]
	s_nop 4
	v_lshl_add_u64 v[150:151], v[150:151], 0, v[148:149]
	s_mov_b64 s[24:25], 0x16000
	v_pk_mul_f32 v[152:153], v[126:127], v[176:177] op_sel_hi:[1,0]
	v_pk_mul_f32 v[154:155], v[128:129], v[176:177] op_sel_hi:[1,0]
	v_pk_mul_f32 v[156:157], v[118:119], v[176:177] op_sel_hi:[1,0]
	v_pk_mul_f32 v[158:159], v[120:121], v[176:177] op_sel_hi:[1,0]
	v_exp_f32_e32 v152, v152
	v_exp_f32_e32 v153, v153
	v_exp_f32_e32 v154, v154
	v_exp_f32_e32 v155, v155
	v_pk_add_f32 v[152:153], v[152:153], 1.0 op_sel_hi:[1,0]
	v_exp_f32_e32 v156, v156
	v_exp_f32_e32 v157, v157
	v_pk_add_f32 v[154:155], v[154:155], 1.0 op_sel_hi:[1,0]
	v_exp_f32_e32 v158, v158
	v_exp_f32_e32 v159, v159
	v_rcp_f32_e32 v152, v152
	v_pk_add_f32 v[156:157], v[156:157], 1.0 op_sel_hi:[1,0]
	v_rcp_f32_e32 v153, v153
	v_rcp_f32_e32 v154, v154
	v_pk_add_f32 v[158:159], v[158:159], 1.0 op_sel_hi:[1,0]
	v_rcp_f32_e32 v155, v155
	v_rcp_f32_e32 v156, v156
	v_pk_mul_f32 v[126:127], v[126:127], v[152:153]
	v_rcp_f32_e32 v157, v157
	v_rcp_f32_e32 v158, v158
	v_pk_mul_f32 v[128:129], v[128:129], v[154:155]
	v_rcp_f32_e32 v159, v159
	v_pk_mul_f32 v[126:127], v[126:127], v[122:123]
	v_pk_mul_f32 v[118:119], v[118:119], v[156:157]
	v_pk_mul_f32 v[128:129], v[128:129], v[124:125]
	v_pk_mul_f32 v[160:161], v[110:111], v[176:177] op_sel_hi:[1,0]
	v_pk_mul_f32 v[120:121], v[120:121], v[158:159]
	v_cvt_pk_bf16_f32 v168, v126, v127
	v_pk_mul_f32 v[118:119], v[118:119], v[114:115]
	v_cvt_pk_bf16_f32 v169, v128, v129
	v_pk_mul_f32 v[120:121], v[120:121], v[116:117]
	v_pk_mul_f32 v[162:163], v[112:113], v[176:177] op_sel_hi:[1,0]
	v_cvt_pk_bf16_f32 v170, v118, v119
	v_pk_mul_f32 v[164:165], v[102:103], v[176:177] op_sel_hi:[1,0]
	v_cvt_pk_bf16_f32 v171, v120, v121
	global_store_dwordx4 v[150:151], v[168:171], off nt
	v_pk_mul_f32 v[166:167], v[104:105], v[176:177] op_sel_hi:[1,0]
	v_exp_f32_e32 v160, v160
	v_exp_f32_e32 v161, v161
	v_exp_f32_e32 v162, v162
	v_exp_f32_e32 v163, v163
	v_pk_add_f32 v[160:161], v[160:161], 1.0 op_sel_hi:[1,0]
	v_exp_f32_e32 v164, v164
	v_exp_f32_e32 v165, v165
	v_pk_add_f32 v[162:163], v[162:163], 1.0 op_sel_hi:[1,0]
	v_exp_f32_e32 v166, v166
	v_exp_f32_e32 v167, v167
	v_rcp_f32_e32 v160, v160
	v_pk_add_f32 v[164:165], v[164:165], 1.0 op_sel_hi:[1,0]
	v_rcp_f32_e32 v161, v161
	v_rcp_f32_e32 v162, v162
	v_pk_add_f32 v[166:167], v[166:167], 1.0 op_sel_hi:[1,0]
	v_rcp_f32_e32 v163, v163
	v_rcp_f32_e32 v164, v164
	v_pk_mul_f32 v[110:111], v[110:111], v[160:161]
	v_rcp_f32_e32 v165, v165
	v_rcp_f32_e32 v166, v166
	v_pk_mul_f32 v[112:113], v[112:113], v[162:163]
	v_rcp_f32_e32 v167, v167
	v_pk_mul_f32 v[110:111], v[110:111], v[106:107]
	v_pk_mul_f32 v[102:103], v[102:103], v[164:165]
	v_pk_mul_f32 v[112:113], v[112:113], v[108:109]
	v_lshl_add_u64 v[178:179], v[150:151], 0, s[24:25]
	v_pk_mul_f32 v[104:105], v[104:105], v[166:167]
	v_cvt_pk_bf16_f32 v172, v110, v111
	v_pk_mul_f32 v[102:103], v[102:103], v[98:99]
	v_cvt_pk_bf16_f32 v173, v112, v113
	v_pk_mul_f32 v[104:105], v[104:105], v[100:101]
	v_pk_mul_f32 v[152:153], v[94:95], v[176:177] op_sel_hi:[1,0]
	v_cvt_pk_bf16_f32 v174, v102, v103
	v_pk_mul_f32 v[154:155], v[96:97], v[176:177] op_sel_hi:[1,0]
	v_cvt_pk_bf16_f32 v175, v104, v105
	global_store_dwordx4 v[178:179], v[172:175], off nt
	v_pk_mul_f32 v[156:157], v[86:87], v[176:177] op_sel_hi:[1,0]
	v_pk_mul_f32 v[158:159], v[88:89], v[176:177] op_sel_hi:[1,0]
	v_exp_f32_e32 v152, v152
	v_exp_f32_e32 v153, v153
	v_exp_f32_e32 v154, v154
	v_exp_f32_e32 v155, v155
	v_pk_add_f32 v[152:153], v[152:153], 1.0 op_sel_hi:[1,0]
	v_exp_f32_e32 v156, v156
	v_exp_f32_e32 v157, v157
	v_pk_add_f32 v[154:155], v[154:155], 1.0 op_sel_hi:[1,0]
	v_exp_f32_e32 v158, v158
	v_exp_f32_e32 v159, v159
	v_rcp_f32_e32 v152, v152
	v_pk_add_f32 v[156:157], v[156:157], 1.0 op_sel_hi:[1,0]
	v_rcp_f32_e32 v153, v153
	v_rcp_f32_e32 v154, v154
	v_pk_add_f32 v[158:159], v[158:159], 1.0 op_sel_hi:[1,0]
	v_rcp_f32_e32 v155, v155
	v_rcp_f32_e32 v156, v156
	v_pk_mul_f32 v[94:95], v[94:95], v[152:153]
	v_rcp_f32_e32 v157, v157
	v_rcp_f32_e32 v158, v158
	v_pk_mul_f32 v[96:97], v[96:97], v[154:155]
	v_rcp_f32_e32 v159, v159
	v_pk_mul_f32 v[94:95], v[94:95], v[90:91]
	v_pk_mul_f32 v[86:87], v[86:87], v[156:157]
	v_pk_mul_f32 v[96:97], v[96:97], v[92:93]
	v_lshl_add_u64 v[150:151], v[178:179], 0, s[24:25]
	v_pk_mul_f32 v[88:89], v[88:89], v[158:159]
	v_cvt_pk_bf16_f32 v168, v94, v95
	v_pk_mul_f32 v[86:87], v[86:87], v[82:83]
	v_cvt_pk_bf16_f32 v169, v96, v97
	v_pk_mul_f32 v[88:89], v[88:89], v[84:85]
	v_pk_mul_f32 v[160:161], v[78:79], v[176:177] op_sel_hi:[1,0]
	v_cvt_pk_bf16_f32 v170, v86, v87
	v_pk_mul_f32 v[162:163], v[80:81], v[176:177] op_sel_hi:[1,0]
	v_cvt_pk_bf16_f32 v171, v88, v89
	global_store_dwordx4 v[150:151], v[168:171], off nt
	v_pk_mul_f32 v[164:165], v[70:71], v[176:177] op_sel_hi:[1,0]
	v_pk_mul_f32 v[166:167], v[72:73], v[176:177] op_sel_hi:[1,0]
	v_exp_f32_e32 v160, v160
	v_exp_f32_e32 v161, v161
	v_exp_f32_e32 v162, v162
	v_exp_f32_e32 v163, v163
	v_pk_add_f32 v[160:161], v[160:161], 1.0 op_sel_hi:[1,0]
	v_exp_f32_e32 v164, v164
	v_exp_f32_e32 v165, v165
	v_pk_add_f32 v[162:163], v[162:163], 1.0 op_sel_hi:[1,0]
	v_exp_f32_e32 v166, v166
	v_exp_f32_e32 v167, v167
	v_rcp_f32_e32 v160, v160
	v_pk_add_f32 v[164:165], v[164:165], 1.0 op_sel_hi:[1,0]
	v_rcp_f32_e32 v161, v161
	v_rcp_f32_e32 v162, v162
; __device__ __forceinline__ unsigned pk2(float lo, float hi) { const f32x2 v = {lo, hi}; const bf16x2n b = __builtin_convertvector(v, bf16x2n); return __builtin_bit_cast(unsigned, b); }
; __device__ __forceinline__ float siluf_(float x) { return x * rcp_(1.0f + __expf(-x)); }
;     __device__ __forceinline__ void operator()(const f32x4 (&acc)[2][2][4][2], const Unit& u, int wr, int wc, int fr, int fq) const {
;     ...
;                 bf16_t* rowp = H + (size_t)(row0 + ai * 128 + m * 16) * DFF + col0;
;                 const f32x4 g0 = acc[ai][0][m][0], g1 = acc[ai][0][m][1], u0 = acc[ai][1][m][0], u1 = acc[ai][1][m][1];
;                 float v[8];
; #pragma unroll
;                 for (int j = 0; j < 4; ++j) { v[j] = siluf_(g0[j]) * u0[j]; v[4 + j] = siluf_(g1[j]) * u1[j]; }
;                 u32x4 w; w.x = pk2(v[0], v[1]); w.y = pk2(v[2], v[3]); w.z = pk2(v[4], v[5]); w.w = pk2(v[6], v[7]);
;                 __builtin_nontemporal_store(w, (u32x4*)rowp);
	v_pk_add_f32 v[166:167], v[166:167], 1.0 op_sel_hi:[1,0]
	v_rcp_f32_e32 v163, v163
	v_rcp_f32_e32 v164, v164
	v_pk_mul_f32 v[78:79], v[78:79], v[160:161]
	v_rcp_f32_e32 v165, v165
	v_rcp_f32_e32 v166, v166
	v_pk_mul_f32 v[80:81], v[80:81], v[162:163]
	v_rcp_f32_e32 v167, v167
	v_pk_mul_f32 v[78:79], v[78:79], v[74:75]
	v_pk_mul_f32 v[70:71], v[70:71], v[164:165]
	v_pk_mul_f32 v[80:81], v[80:81], v[76:77]
	v_lshl_add_u64 v[178:179], v[150:151], 0, s[24:25]
	v_pk_mul_f32 v[72:73], v[72:73], v[166:167]
	v_cvt_pk_bf16_f32 v172, v78, v79
	v_pk_mul_f32 v[70:71], v[70:71], v[66:67]
	v_cvt_pk_bf16_f32 v173, v80, v81
	v_pk_mul_f32 v[72:73], v[72:73], v[68:69]
	v_pk_mul_f32 v[152:153], v[62:63], v[176:177] op_sel_hi:[1,0]
	v_cvt_pk_bf16_f32 v174, v70, v71
	v_pk_mul_f32 v[154:155], v[64:65], v[176:177] op_sel_hi:[1,0]
	v_cvt_pk_bf16_f32 v175, v72, v73
	global_store_dwordx4 v[178:179], v[172:175], off nt
	v_pk_mul_f32 v[156:157], v[54:55], v[176:177] op_sel_hi:[1,0]
	v_pk_mul_f32 v[158:159], v[56:57], v[176:177] op_sel_hi:[1,0]
	v_exp_f32_e32 v152, v152
	v_exp_f32_e32 v153, v153
	v_exp_f32_e32 v154, v154
	v_exp_f32_e32 v155, v155
	v_pk_add_f32 v[152:153], v[152:153], 1.0 op_sel_hi:[1,0]
	v_exp_f32_e32 v156, v156
	v_exp_f32_e32 v157, v157
	v_pk_add_f32 v[154:155], v[154:155], 1.0 op_sel_hi:[1,0]
	v_exp_f32_e32 v158, v158
	v_exp_f32_e32 v159, v159
	v_rcp_f32_e32 v152, v152
	v_pk_add_f32 v[156:157], v[156:157], 1.0 op_sel_hi:[1,0]
	v_rcp_f32_e32 v153, v153
	v_rcp_f32_e32 v154, v154
	v_pk_add_f32 v[158:159], v[158:159], 1.0 op_sel_hi:[1,0]
	v_rcp_f32_e32 v155, v155
	v_rcp_f32_e32 v156, v156
	v_pk_mul_f32 v[62:63], v[62:63], v[152:153]
	v_rcp_f32_e32 v157, v157
	v_rcp_f32_e32 v158, v158
	v_pk_mul_f32 v[64:65], v[64:65], v[154:155]
	v_rcp_f32_e32 v159, v159
	v_pk_mul_f32 v[62:63], v[62:63], v[58:59]
	v_pk_mul_f32 v[54:55], v[54:55], v[156:157]
	v_pk_mul_f32 v[64:65], v[64:65], v[60:61]
	s_mov_b64 s[24:25], 0x6e000
	v_lshl_add_u64 v[150:151], v[178:179], 0, s[24:25]
	s_mov_b64 s[24:25], 0x16000
	v_pk_mul_f32 v[56:57], v[56:57], v[158:159]
	v_cvt_pk_bf16_f32 v168, v62, v63
	v_pk_mul_f32 v[54:55], v[54:55], v[50:51]
	v_cvt_pk_bf16_f32 v169, v64, v65
	v_pk_mul_f32 v[56:57], v[56:57], v[52:53]
	v_pk_mul_f32 v[160:161], v[46:47], v[176:177] op_sel_hi:[1,0]
	v_cvt_pk_bf16_f32 v170, v54, v55
	v_pk_mul_f32 v[162:163], v[48:49], v[176:177] op_sel_hi:[1,0]
	v_cvt_pk_bf16_f32 v171, v56, v57
	global_store_dwordx4 v[150:151], v[168:171], off nt
	v_pk_mul_f32 v[164:165], v[38:39], v[176:177] op_sel_hi:[1,0]
	v_pk_mul_f32 v[166:167], v[40:41], v[176:177] op_sel_hi:[1,0]
	v_exp_f32_e32 v160, v160
	v_exp_f32_e32 v161, v161
	v_exp_f32_e32 v162, v162
	v_exp_f32_e32 v163, v163
	v_pk_add_f32 v[160:161], v[160:161], 1.0 op_sel_hi:[1,0]
	v_exp_f32_e32 v164, v164
	v_exp_f32_e32 v165, v165
	v_pk_add_f32 v[162:163], v[162:163], 1.0 op_sel_hi:[1,0]
	v_exp_f32_e32 v166, v166
	v_exp_f32_e32 v167, v167
	v_rcp_f32_e32 v160, v160
	v_pk_add_f32 v[164:165], v[164:165], 1.0 op_sel_hi:[1,0]
	v_rcp_f32_e32 v161, v161
	v_rcp_f32_e32 v162, v162
	v_pk_add_f32 v[166:167], v[166:167], 1.0 op_sel_hi:[1,0]
	v_rcp_f32_e32 v163, v163
	v_rcp_f32_e32 v164, v164
	v_pk_mul_f32 v[46:47], v[46:47], v[160:161]
	v_rcp_f32_e32 v165, v165
	v_rcp_f32_e32 v166, v166
	v_pk_mul_f32 v[48:49], v[48:49], v[162:163]
	v_rcp_f32_e32 v167, v167
	v_pk_mul_f32 v[46:47], v[46:47], v[42:43]
	v_pk_mul_f32 v[38:39], v[38:39], v[164:165]
	v_pk_mul_f32 v[48:49], v[48:49], v[44:45]
	v_lshl_add_u64 v[178:179], v[150:151], 0, s[24:25]
	v_pk_mul_f32 v[40:41], v[40:41], v[166:167]
	v_cvt_pk_bf16_f32 v172, v46, v47
	v_pk_mul_f32 v[38:39], v[38:39], v[34:35]
	v_cvt_pk_bf16_f32 v173, v48, v49
	v_pk_mul_f32 v[40:41], v[40:41], v[36:37]
	v_pk_mul_f32 v[152:153], v[30:31], v[176:177] op_sel_hi:[1,0]
	v_cvt_pk_bf16_f32 v174, v38, v39
	v_pk_mul_f32 v[154:155], v[32:33], v[176:177] op_sel_hi:[1,0]
	v_cvt_pk_bf16_f32 v175, v40, v41
	global_store_dwordx4 v[178:179], v[172:175], off nt
	v_pk_mul_f32 v[156:157], v[22:23], v[176:177] op_sel_hi:[1,0]
	v_pk_mul_f32 v[158:159], v[24:25], v[176:177] op_sel_hi:[1,0]
	v_exp_f32_e32 v152, v152
	v_exp_f32_e32 v153, v153
	v_exp_f32_e32 v154, v154
	v_exp_f32_e32 v155, v155
	v_pk_add_f32 v[152:153], v[152:153], 1.0 op_sel_hi:[1,0]
	v_exp_f32_e32 v156, v156
	v_exp_f32_e32 v157, v157
	v_pk_add_f32 v[154:155], v[154:155], 1.0 op_sel_hi:[1,0]
	v_exp_f32_e32 v158, v158
	v_exp_f32_e32 v159, v159
	v_rcp_f32_e32 v152, v152
	v_pk_add_f32 v[156:157], v[156:157], 1.0 op_sel_hi:[1,0]
	v_rcp_f32_e32 v153, v153
	v_rcp_f32_e32 v154, v154
	v_pk_add_f32 v[158:159], v[158:159], 1.0 op_sel_hi:[1,0]
	v_rcp_f32_e32 v155, v155
	v_rcp_f32_e32 v156, v156
	v_pk_mul_f32 v[30:31], v[30:31], v[152:153]
	v_rcp_f32_e32 v157, v157
	v_rcp_f32_e32 v158, v158
	v_pk_mul_f32 v[32:33], v[32:33], v[154:155]
	v_rcp_f32_e32 v159, v159
	v_pk_mul_f32 v[30:31], v[30:31], v[26:27]
	v_pk_mul_f32 v[22:23], v[22:23], v[156:157]
	v_pk_mul_f32 v[32:33], v[32:33], v[28:29]
	v_lshl_add_u64 v[150:151], v[178:179], 0, s[24:25]
	v_pk_mul_f32 v[24:25], v[24:25], v[158:159]
	v_cvt_pk_bf16_f32 v168, v30, v31
	v_pk_mul_f32 v[22:23], v[22:23], v[18:19]
	v_cvt_pk_bf16_f32 v169, v32, v33
	v_pk_mul_f32 v[24:25], v[24:25], v[20:21]
	v_pk_mul_f32 v[160:161], v[14:15], v[176:177] op_sel_hi:[1,0]
	v_cvt_pk_bf16_f32 v170, v22, v23
	v_pk_mul_f32 v[162:163], v[16:17], v[176:177] op_sel_hi:[1,0]
	v_cvt_pk_bf16_f32 v171, v24, v25
	global_store_dwordx4 v[150:151], v[168:171], off nt
	v_pk_mul_f32 v[164:165], v[6:7], v[176:177] op_sel_hi:[1,0]
	v_pk_mul_f32 v[166:167], v[8:9], v[176:177] op_sel_hi:[1,0]
	v_exp_f32_e32 v160, v160
	v_exp_f32_e32 v161, v161
	v_exp_f32_e32 v162, v162
	v_exp_f32_e32 v163, v163
	v_pk_add_f32 v[160:161], v[160:161], 1.0 op_sel_hi:[1,0]
	v_exp_f32_e32 v164, v164
	v_exp_f32_e32 v165, v165
	v_pk_add_f32 v[162:163], v[162:163], 1.0 op_sel_hi:[1,0]
	v_exp_f32_e32 v166, v166
	v_exp_f32_e32 v167, v167
	v_rcp_f32_e32 v160, v160
	v_pk_add_f32 v[164:165], v[164:165], 1.0 op_sel_hi:[1,0]
	v_rcp_f32_e32 v161, v161
	v_rcp_f32_e32 v162, v162
	v_pk_add_f32 v[166:167], v[166:167], 1.0 op_sel_hi:[1,0]
	v_rcp_f32_e32 v163, v163
	v_rcp_f32_e32 v164, v164
	v_pk_mul_f32 v[14:15], v[14:15], v[160:161]
	v_rcp_f32_e32 v165, v165
	v_rcp_f32_e32 v166, v166
	v_pk_mul_f32 v[16:17], v[16:17], v[162:163]
	v_rcp_f32_e32 v167, v167
	v_pk_mul_f32 v[14:15], v[14:15], v[10:11]
	v_pk_mul_f32 v[6:7], v[6:7], v[164:165]
	v_pk_mul_f32 v[16:17], v[16:17], v[12:13]
	v_lshl_add_u64 v[178:179], v[150:151], 0, s[24:25]
	v_pk_mul_f32 v[8:9], v[8:9], v[166:167]
	v_cvt_pk_bf16_f32 v172, v14, v15
	v_pk_mul_f32 v[6:7], v[6:7], v[2:3]
	v_cvt_pk_bf16_f32 v173, v16, v17
	v_pk_mul_f32 v[8:9], v[8:9], v[4:5]
	s_nop 0
	v_cvt_pk_bf16_f32 v174, v6, v7
	s_nop 0
	v_cvt_pk_bf16_f32 v175, v8, v9
	global_store_dwordx4 v[178:179], v[172:175], off nt
	s_mov_b64 s[24:25], -1
	s_andn2_b64 vcc, exec, s[10:11]
	s_cbranch_vccnz .LBB0_780
	s_andn2_b64 vcc, exec, s[12:13]
	s_cbranch_vccnz .LBB0_779
	s_barrier
	s_branch .LBB0_779
